# v17 + E2 q/k-norm epilogue: gain vectors loaded once (8 loads up front) instead of 24 loads each behind vmcnt(0)
# baseline (speedup 1.0000x reference)
.LBB0_862:
	s_or_b64 exec, exec, s[6:7]
	v_mov_b32_e32 v72, s9
	v_mov_b32_e32 v73, s11
	v_cndmask_b32_e32 v73, v72, v73, vcc
	v_mov_b32_e32 v72, s8
	v_mov_b32_e32 v74, s10
	v_cndmask_b32_e32 v72, v72, v74, vcc
	v_mov_b32_e32 v74, s19
	v_mov_b32_e32 v75, s25
	v_cndmask_b32_e32 v75, v74, v75, vcc
	v_mov_b32_e32 v74, s18
	v_mov_b32_e32 v78, s24
	v_ashrrev_i32_e32 v117, 31, v116
	v_cndmask_b32_e32 v74, v74, v78, vcc
	v_lshlrev_b64 v[78:79], 10, v[116:117]
	v_lshl_add_u64 v[74:75], v[74:75], 0, v[78:79]
	v_lshl_add_u64 v[92:93], v[108:109], 1, v[74:75]
	v_mul_f32_e32 v74, v105, v105
	v_pk_fma_f32 v[74:75], v[104:105], v[104:105], v[74:75] op_sel_hi:[1,1,0]
	v_mul_f32_e32 v78, v107, v107
	v_pk_fma_f32 v[74:75], v[106:107], v[106:107], v[74:75]
	s_mov_b32 s6, 0x800000
	v_pk_add_f32 v[74:75], v[78:79], v[74:75] op_sel_hi:[0,1]
	v_pk_fma_f32 v[74:75], v[100:101], v[100:101], v[74:75]
	v_mul_f32_e32 v78, v101, v101
	v_pk_add_f32 v[74:75], v[78:79], v[74:75] op_sel_hi:[0,1]
	v_pk_fma_f32 v[74:75], v[102:103], v[102:103], v[74:75]
	v_mul_f32_e32 v78, v103, v103
	v_pk_add_f32 v[74:75], v[78:79], v[74:75] op_sel_hi:[0,1]
	v_pk_fma_f32 v[74:75], v[96:97], v[96:97], v[74:75]
	v_mul_f32_e32 v78, v97, v97
	v_pk_add_f32 v[74:75], v[78:79], v[74:75] op_sel_hi:[0,1]
	v_pk_fma_f32 v[74:75], v[98:99], v[98:99], v[74:75]
	v_mul_f32_e32 v78, v99, v99
	v_pk_add_f32 v[74:75], v[78:79], v[74:75] op_sel_hi:[0,1]
	v_pk_fma_f32 v[74:75], v[88:89], v[88:89], v[74:75]
	v_mul_f32_e32 v78, v89, v89
	v_pk_add_f32 v[74:75], v[78:79], v[74:75] op_sel_hi:[0,1]
	v_pk_fma_f32 v[74:75], v[90:91], v[90:91], v[74:75]
	v_mul_f32_e32 v78, v91, v91
	v_pk_add_f32 v[74:75], v[78:79], v[74:75] op_sel_hi:[0,1]
	v_pk_fma_f32 v[74:75], v[84:85], v[84:85], v[74:75]
	v_mul_f32_e32 v78, v85, v85
	v_pk_add_f32 v[74:75], v[78:79], v[74:75] op_sel_hi:[0,1]
	v_pk_fma_f32 v[74:75], v[86:87], v[86:87], v[74:75]
	v_mul_f32_e32 v78, v87, v87
	v_pk_add_f32 v[74:75], v[78:79], v[74:75] op_sel_hi:[0,1]
	v_pk_fma_f32 v[74:75], v[80:81], v[80:81], v[74:75]
	v_mul_f32_e32 v78, v81, v81
	v_pk_add_f32 v[74:75], v[78:79], v[74:75] op_sel_hi:[0,1]
	v_pk_fma_f32 v[74:75], v[82:83], v[82:83], v[74:75]
	v_mul_f32_e32 v78, v83, v83
	v_pk_add_f32 v[74:75], v[78:79], v[74:75] op_sel_hi:[0,1]
	v_pk_fma_f32 v[74:75], v[68:69], v[68:69], v[74:75]
	v_mul_f32_e32 v78, v69, v69
	v_pk_add_f32 v[74:75], v[78:79], v[74:75] op_sel_hi:[0,1]
	v_pk_fma_f32 v[74:75], v[70:71], v[70:71], v[74:75]
	v_mul_f32_e32 v78, v71, v71
	v_pk_add_f32 v[74:75], v[78:79], v[74:75] op_sel_hi:[0,1]
	v_pk_fma_f32 v[74:75], v[64:65], v[64:65], v[74:75]
	v_mul_f32_e32 v78, v65, v65
	v_pk_add_f32 v[74:75], v[78:79], v[74:75] op_sel_hi:[0,1]
	v_pk_fma_f32 v[74:75], v[66:67], v[66:67], v[74:75]
	v_mul_f32_e32 v78, v67, v67
	v_pk_add_f32 v[74:75], v[78:79], v[74:75] op_sel_hi:[0,1]
	v_mov_b32_e32 v75, v74
	s_nop 1
	v_permlane32_swap_b32_e32 v74, v75
	v_add_f32_e32 v74, v74, v75
	v_fmamk_f32 v74, v74, 0x3c800000, v163
	v_cmp_gt_f32_e64 s[42:43], s6, v74
	v_mul_f32_e32 v75, 0x4b800000, v74
	v_lshlrev_b32_e32 v128, 2, v118
	v_cndmask_b32_e64 v74, v74, v75, s[42:43]
	v_rsq_f32_e32 v74, v74
	v_lshl_add_u64 v[94:95], v[72:73], 0, v[128:129]
	v_mul_f32_e32 v75, 0x45800000, v74
	v_cndmask_b32_e64 v78, v74, v75, s[42:43]
	global_load_dwordx4 v[198:201], v[94:95], off
	global_load_dwordx4 v[202:205], v[94:95], off offset:32
	global_load_dwordx4 v[206:209], v[94:95], off offset:64
	global_load_dwordx4 v[210:213], v[94:95], off offset:96
	global_load_dwordx4 v[214:217], v[94:95], off offset:128
	global_load_dwordx4 v[218:221], v[94:95], off offset:160
	global_load_dwordx4 v[222:225], v[94:95], off offset:192
	global_load_dwordx4 v[226:229], v[94:95], off offset:224
	v_pk_mul_f32 v[104:105], v[104:105], v[78:79] op_sel_hi:[1,0]
	v_cmp_ne_u64_e64 s[42:43], 0, v[76:77]
	s_waitcnt vmcnt(7)
	v_pk_mul_f32 v[72:73], v[198:199], v[104:105]
	v_pk_mul_f32 v[104:105], v[106:107], v[78:79] op_sel_hi:[1,0]
	s_nop 0
	v_pk_mul_f32 v[74:75], v[200:201], v[104:105]
	v_lshlrev_b32_e32 v104, 1, v118
	v_mov_b32_e32 v105, v129
	v_lshl_add_u64 v[92:93], v[92:93], 0, v[104:105]
	v_cvt_pk_bf16_f32 v104, v72, v73
	v_cvt_pk_bf16_f32 v105, v74, v75
	global_store_dwordx2 v[92:93], v[104:105], off
	s_and_saveexec_b64 s[6:7], s[42:43]
	s_cbranch_execz .LBB0_864
	v_lshl_add_u64 v[104:105], v[76:77], 0, v[128:129]
	global_store_dwordx4 v[104:105], v[72:75], off
.LBB0_864:
	s_or_b64 exec, exec, s[6:7]
	v_mov_b32_e32 v79, v78
	v_pk_mul_f32 v[100:101], v[100:101], v[78:79]
	v_pk_mul_f32 v[102:103], v[102:103], v[78:79]
	s_waitcnt vmcnt(7)
	v_pk_mul_f32 v[72:73], v[100:101], v[202:203]
	v_pk_mul_f32 v[74:75], v[102:103], v[204:205]
	v_cvt_pk_bf16_f32 v100, v72, v73
	v_cvt_pk_bf16_f32 v101, v74, v75
	global_store_dwordx2 v[92:93], v[100:101], off offset:16
	s_and_saveexec_b64 s[6:7], s[42:43]
	s_cbranch_execz .LBB0_866
	v_lshl_add_u64 v[100:101], v[76:77], 0, v[128:129]
	global_store_dwordx4 v[100:101], v[72:75], off offset:32
.LBB0_866:
	s_or_b64 exec, exec, s[6:7]
	v_pk_mul_f32 v[96:97], v[96:97], v[78:79]
	v_pk_mul_f32 v[98:99], v[98:99], v[78:79]
	s_waitcnt vmcnt(7)
	v_pk_mul_f32 v[72:73], v[96:97], v[206:207]
	v_pk_mul_f32 v[74:75], v[98:99], v[208:209]
	v_cvt_pk_bf16_f32 v96, v72, v73
	v_cvt_pk_bf16_f32 v97, v74, v75
	global_store_dwordx2 v[92:93], v[96:97], off offset:32
	s_and_saveexec_b64 s[6:7], s[42:43]
	s_cbranch_execz .LBB0_868
	v_lshl_add_u64 v[96:97], v[76:77], 0, v[128:129]
	global_store_dwordx4 v[96:97], v[72:75], off offset:64
.LBB0_868:
	s_or_b64 exec, exec, s[6:7]
	v_pk_mul_f32 v[88:89], v[88:89], v[78:79]
	v_pk_mul_f32 v[90:91], v[90:91], v[78:79]
	s_waitcnt vmcnt(7)
	v_pk_mul_f32 v[72:73], v[88:89], v[210:211]
	v_pk_mul_f32 v[74:75], v[90:91], v[212:213]
	v_cvt_pk_bf16_f32 v88, v72, v73
	v_cvt_pk_bf16_f32 v89, v74, v75
	global_store_dwordx2 v[92:93], v[88:89], off offset:48
	s_and_saveexec_b64 s[6:7], s[42:43]
	s_cbranch_execz .LBB0_870
	v_lshl_add_u64 v[88:89], v[76:77], 0, v[128:129]
	global_store_dwordx4 v[88:89], v[72:75], off offset:96
.LBB0_870:
	s_or_b64 exec, exec, s[6:7]
	v_pk_mul_f32 v[84:85], v[84:85], v[78:79]
	v_pk_mul_f32 v[86:87], v[86:87], v[78:79]
	s_waitcnt vmcnt(7)
	v_pk_mul_f32 v[72:73], v[84:85], v[214:215]
	v_pk_mul_f32 v[74:75], v[86:87], v[216:217]
	v_cvt_pk_bf16_f32 v84, v72, v73
	v_cvt_pk_bf16_f32 v85, v74, v75
	global_store_dwordx2 v[92:93], v[84:85], off offset:64
	s_and_saveexec_b64 s[6:7], s[42:43]
	s_cbranch_execz .LBB0_872
	v_lshl_add_u64 v[84:85], v[76:77], 0, v[128:129]
	global_store_dwordx4 v[84:85], v[72:75], off offset:128
.LBB0_872:
	s_or_b64 exec, exec, s[6:7]
	v_pk_mul_f32 v[80:81], v[80:81], v[78:79]
	v_pk_mul_f32 v[82:83], v[82:83], v[78:79]
	s_waitcnt vmcnt(7)
	v_pk_mul_f32 v[72:73], v[80:81], v[218:219]
	v_pk_mul_f32 v[74:75], v[82:83], v[220:221]
	v_cvt_pk_bf16_f32 v80, v72, v73
	v_cvt_pk_bf16_f32 v81, v74, v75
	global_store_dwordx2 v[92:93], v[80:81], off offset:80
	s_and_saveexec_b64 s[6:7], s[42:43]
	s_cbranch_execz .LBB0_874
	v_lshl_add_u64 v[80:81], v[76:77], 0, v[128:129]
	global_store_dwordx4 v[80:81], v[72:75], off offset:160
.LBB0_874:
	s_or_b64 exec, exec, s[6:7]
	v_pk_mul_f32 v[68:69], v[68:69], v[78:79]
	v_pk_mul_f32 v[70:71], v[70:71], v[78:79]
	s_waitcnt vmcnt(7)
	v_pk_mul_f32 v[68:69], v[68:69], v[222:223]
	v_pk_mul_f32 v[70:71], v[70:71], v[224:225]
	v_cvt_pk_bf16_f32 v72, v68, v69
	v_cvt_pk_bf16_f32 v73, v70, v71
	global_store_dwordx2 v[92:93], v[72:73], off offset:96
	s_and_saveexec_b64 s[6:7], s[42:43]
	s_cbranch_execz .LBB0_876
	v_lshl_add_u64 v[72:73], v[76:77], 0, v[128:129]
	global_store_dwordx4 v[72:73], v[68:71], off offset:192
.LBB0_876:
	s_or_b64 exec, exec, s[6:7]
	v_pk_mul_f32 v[64:65], v[64:65], v[78:79]
	v_pk_mul_f32 v[66:67], v[66:67], v[78:79]
	s_waitcnt vmcnt(7)
	v_pk_mul_f32 v[64:65], v[64:65], v[226:227]
	v_pk_mul_f32 v[66:67], v[66:67], v[228:229]
	v_cvt_pk_bf16_f32 v68, v64, v65
	v_cvt_pk_bf16_f32 v69, v66, v67
	global_store_dwordx2 v[92:93], v[68:69], off offset:112
	s_and_saveexec_b64 s[6:7], s[42:43]
	s_cbranch_execz .LBB0_878
	v_lshl_add_u64 v[68:69], v[76:77], 0, v[128:129]
	global_store_dwordx4 v[68:69], v[64:67], off offset:224

.LBB0_910:
	s_or_b64 exec, exec, s[6:7]
	v_mov_b32_e32 v40, s9
	v_mov_b32_e32 v41, s11
	v_cndmask_b32_e32 v41, v40, v41, vcc
	v_mov_b32_e32 v40, s8
	v_mov_b32_e32 v42, s10
	v_cndmask_b32_e32 v40, v40, v42, vcc
	v_mov_b32_e32 v42, s19
	v_mov_b32_e32 v43, s25
	v_cndmask_b32_e32 v43, v42, v43, vcc
	v_mov_b32_e32 v42, s18
	v_mov_b32_e32 v46, s24
	v_ashrrev_i32_e32 v79, 31, v78
	v_cndmask_b32_e32 v42, v42, v46, vcc
	v_lshlrev_b64 v[46:47], 10, v[78:79]
	v_lshl_add_u64 v[42:43], v[42:43], 0, v[46:47]
	v_lshl_add_u64 v[60:61], v[108:109], 1, v[42:43]
	v_mul_f32_e32 v42, v73, v73
	v_pk_fma_f32 v[42:43], v[72:73], v[72:73], v[42:43] op_sel_hi:[1,1,0]
	v_mul_f32_e32 v46, v75, v75
	v_pk_fma_f32 v[42:43], v[74:75], v[74:75], v[42:43]
	s_mov_b32 s6, 0x800000
	v_pk_add_f32 v[42:43], v[46:47], v[42:43] op_sel_hi:[0,1]
	v_pk_fma_f32 v[42:43], v[68:69], v[68:69], v[42:43]
	v_mul_f32_e32 v46, v69, v69
	v_pk_add_f32 v[42:43], v[46:47], v[42:43] op_sel_hi:[0,1]
	v_pk_fma_f32 v[42:43], v[70:71], v[70:71], v[42:43]
	v_mul_f32_e32 v46, v71, v71
	v_pk_add_f32 v[42:43], v[46:47], v[42:43] op_sel_hi:[0,1]
	v_pk_fma_f32 v[42:43], v[64:65], v[64:65], v[42:43]
	v_mul_f32_e32 v46, v65, v65
	v_pk_add_f32 v[42:43], v[46:47], v[42:43] op_sel_hi:[0,1]
	v_pk_fma_f32 v[42:43], v[66:67], v[66:67], v[42:43]
	v_mul_f32_e32 v46, v67, v67
	v_pk_add_f32 v[42:43], v[46:47], v[42:43] op_sel_hi:[0,1]
	v_pk_fma_f32 v[42:43], v[56:57], v[56:57], v[42:43]
	v_mul_f32_e32 v46, v57, v57
	v_pk_add_f32 v[42:43], v[46:47], v[42:43] op_sel_hi:[0,1]
	v_pk_fma_f32 v[42:43], v[58:59], v[58:59], v[42:43]
	v_mul_f32_e32 v46, v59, v59
	v_pk_add_f32 v[42:43], v[46:47], v[42:43] op_sel_hi:[0,1]
	v_pk_fma_f32 v[42:43], v[52:53], v[52:53], v[42:43]
	v_mul_f32_e32 v46, v53, v53
	v_pk_add_f32 v[42:43], v[46:47], v[42:43] op_sel_hi:[0,1]
	v_pk_fma_f32 v[42:43], v[54:55], v[54:55], v[42:43]
	v_mul_f32_e32 v46, v55, v55
	v_pk_add_f32 v[42:43], v[46:47], v[42:43] op_sel_hi:[0,1]
	v_pk_fma_f32 v[42:43], v[48:49], v[48:49], v[42:43]
	v_mul_f32_e32 v46, v49, v49
	v_pk_add_f32 v[42:43], v[46:47], v[42:43] op_sel_hi:[0,1]
	v_pk_fma_f32 v[42:43], v[50:51], v[50:51], v[42:43]
	v_mul_f32_e32 v46, v51, v51
	v_pk_add_f32 v[42:43], v[46:47], v[42:43] op_sel_hi:[0,1]
	v_pk_fma_f32 v[42:43], v[36:37], v[36:37], v[42:43]
	v_mul_f32_e32 v46, v37, v37
	v_pk_add_f32 v[42:43], v[46:47], v[42:43] op_sel_hi:[0,1]
	v_pk_fma_f32 v[42:43], v[38:39], v[38:39], v[42:43]
	v_mul_f32_e32 v46, v39, v39
	v_pk_add_f32 v[42:43], v[46:47], v[42:43] op_sel_hi:[0,1]
	v_pk_fma_f32 v[42:43], v[32:33], v[32:33], v[42:43]
	v_mul_f32_e32 v46, v33, v33
	v_pk_add_f32 v[42:43], v[46:47], v[42:43] op_sel_hi:[0,1]
	v_pk_fma_f32 v[42:43], v[34:35], v[34:35], v[42:43]
	v_mul_f32_e32 v46, v35, v35
	v_pk_add_f32 v[42:43], v[46:47], v[42:43] op_sel_hi:[0,1]
	v_mov_b32_e32 v43, v42
	s_nop 1
	v_permlane32_swap_b32_e32 v42, v43
	v_add_f32_e32 v42, v42, v43
	v_fmamk_f32 v42, v42, 0x3c800000, v163
	v_cmp_gt_f32_e64 s[42:43], s6, v42
	v_mul_f32_e32 v43, 0x4b800000, v42
	v_lshlrev_b32_e32 v128, 2, v118
	v_cndmask_b32_e64 v42, v42, v43, s[42:43]
	v_rsq_f32_e32 v42, v42
	v_lshl_add_u64 v[62:63], v[40:41], 0, v[128:129]
	v_mov_b32_e32 v77, v129
	v_lshl_add_u64 v[60:61], v[60:61], 0, v[76:77]
	v_mul_f32_e32 v43, 0x45800000, v42
	v_cndmask_b32_e64 v46, v42, v43, s[42:43]
	v_pk_mul_f32 v[72:73], v[72:73], v[46:47] op_sel_hi:[1,0]
	v_cmp_ne_u64_e64 s[42:43], 0, v[44:45]
	s_nop 0
	v_pk_mul_f32 v[40:41], v[198:199], v[72:73]
	v_pk_mul_f32 v[72:73], v[74:75], v[46:47] op_sel_hi:[1,0]
	s_nop 0
	v_pk_mul_f32 v[42:43], v[200:201], v[72:73]
	v_cvt_pk_bf16_f32 v72, v40, v41
	v_cvt_pk_bf16_f32 v73, v42, v43
	global_store_dwordx2 v[60:61], v[72:73], off
	s_and_saveexec_b64 s[6:7], s[42:43]
	s_cbranch_execz .LBB0_912
	v_lshl_add_u64 v[72:73], v[44:45], 0, v[128:129]
	global_store_dwordx4 v[72:73], v[40:43], off
.LBB0_912:
	s_or_b64 exec, exec, s[6:7]
	v_mov_b32_e32 v47, v46
	v_pk_mul_f32 v[68:69], v[68:69], v[46:47]
	v_pk_mul_f32 v[70:71], v[70:71], v[46:47]
	s_nop 0
	v_pk_mul_f32 v[40:41], v[68:69], v[202:203]
	v_pk_mul_f32 v[42:43], v[70:71], v[204:205]
	v_cvt_pk_bf16_f32 v68, v40, v41
	v_cvt_pk_bf16_f32 v69, v42, v43
	global_store_dwordx2 v[60:61], v[68:69], off offset:16
	s_and_saveexec_b64 s[6:7], s[42:43]
	s_cbranch_execz .LBB0_914
	v_lshl_add_u64 v[68:69], v[44:45], 0, v[128:129]
	global_store_dwordx4 v[68:69], v[40:43], off offset:32
.LBB0_914:
	s_or_b64 exec, exec, s[6:7]
	v_pk_mul_f32 v[64:65], v[64:65], v[46:47]
	v_pk_mul_f32 v[66:67], v[66:67], v[46:47]
	s_nop 0
	v_pk_mul_f32 v[40:41], v[64:65], v[206:207]
	v_pk_mul_f32 v[42:43], v[66:67], v[208:209]
	v_cvt_pk_bf16_f32 v64, v40, v41
	v_cvt_pk_bf16_f32 v65, v42, v43
	global_store_dwordx2 v[60:61], v[64:65], off offset:32
	s_and_saveexec_b64 s[6:7], s[42:43]
	s_cbranch_execz .LBB0_916
	v_lshl_add_u64 v[64:65], v[44:45], 0, v[128:129]
	global_store_dwordx4 v[64:65], v[40:43], off offset:64
.LBB0_916:
	s_or_b64 exec, exec, s[6:7]
	v_pk_mul_f32 v[56:57], v[56:57], v[46:47]
	v_pk_mul_f32 v[58:59], v[58:59], v[46:47]
	s_nop 0
	v_pk_mul_f32 v[40:41], v[56:57], v[210:211]
	v_pk_mul_f32 v[42:43], v[58:59], v[212:213]
	v_cvt_pk_bf16_f32 v56, v40, v41
	v_cvt_pk_bf16_f32 v57, v42, v43
	global_store_dwordx2 v[60:61], v[56:57], off offset:48
	s_and_saveexec_b64 s[6:7], s[42:43]
	s_cbranch_execz .LBB0_918
	v_lshl_add_u64 v[56:57], v[44:45], 0, v[128:129]
	global_store_dwordx4 v[56:57], v[40:43], off offset:96
.LBB0_918:
	s_or_b64 exec, exec, s[6:7]
	v_pk_mul_f32 v[52:53], v[52:53], v[46:47]
	v_pk_mul_f32 v[54:55], v[54:55], v[46:47]
	s_nop 0
	v_pk_mul_f32 v[40:41], v[52:53], v[214:215]
	v_pk_mul_f32 v[42:43], v[54:55], v[216:217]
	v_cvt_pk_bf16_f32 v52, v40, v41
	v_cvt_pk_bf16_f32 v53, v42, v43
	global_store_dwordx2 v[60:61], v[52:53], off offset:64
	s_and_saveexec_b64 s[6:7], s[42:43]
	s_cbranch_execz .LBB0_920
	v_lshl_add_u64 v[52:53], v[44:45], 0, v[128:129]
	global_store_dwordx4 v[52:53], v[40:43], off offset:128
.LBB0_920:
	s_or_b64 exec, exec, s[6:7]
	v_pk_mul_f32 v[48:49], v[48:49], v[46:47]
	v_pk_mul_f32 v[50:51], v[50:51], v[46:47]
	s_nop 0
	v_pk_mul_f32 v[40:41], v[48:49], v[218:219]
	v_pk_mul_f32 v[42:43], v[50:51], v[220:221]
	v_cvt_pk_bf16_f32 v48, v40, v41
	v_cvt_pk_bf16_f32 v49, v42, v43
	global_store_dwordx2 v[60:61], v[48:49], off offset:80
	s_and_saveexec_b64 s[6:7], s[42:43]
	s_cbranch_execz .LBB0_922
	v_lshl_add_u64 v[48:49], v[44:45], 0, v[128:129]
	global_store_dwordx4 v[48:49], v[40:43], off offset:160
.LBB0_922:
	s_or_b64 exec, exec, s[6:7]
	v_pk_mul_f32 v[36:37], v[36:37], v[46:47]
	v_pk_mul_f32 v[38:39], v[38:39], v[46:47]
	s_nop 0
	v_pk_mul_f32 v[36:37], v[36:37], v[222:223]
	v_pk_mul_f32 v[38:39], v[38:39], v[224:225]
	v_cvt_pk_bf16_f32 v40, v36, v37
	v_cvt_pk_bf16_f32 v41, v38, v39
	global_store_dwordx2 v[60:61], v[40:41], off offset:96
	s_and_saveexec_b64 s[6:7], s[42:43]
	s_cbranch_execz .LBB0_924
	v_lshl_add_u64 v[40:41], v[44:45], 0, v[128:129]
	global_store_dwordx4 v[40:41], v[36:39], off offset:192
.LBB0_924:
	s_or_b64 exec, exec, s[6:7]
	v_pk_mul_f32 v[32:33], v[32:33], v[46:47]
	v_pk_mul_f32 v[34:35], v[34:35], v[46:47]
	s_nop 0
	v_pk_mul_f32 v[32:33], v[32:33], v[226:227]
	v_pk_mul_f32 v[34:35], v[34:35], v[228:229]
	v_cvt_pk_bf16_f32 v36, v32, v33
	v_cvt_pk_bf16_f32 v37, v34, v35
	global_store_dwordx2 v[60:61], v[36:37], off offset:112
	s_and_saveexec_b64 s[6:7], s[42:43]
	s_cbranch_execz .LBB0_926
	v_lshl_add_u64 v[36:37], v[44:45], 0, v[128:129]
	global_store_dwordx4 v[36:37], v[32:35], off offset:224

.LBB0_958:
	s_or_b64 exec, exec, s[4:5]
	v_mov_b32_e32 v16, s9
	v_mov_b32_e32 v17, s11
	v_cndmask_b32_e32 v17, v16, v17, vcc
	v_mov_b32_e32 v16, s8
	v_mov_b32_e32 v18, s10
	v_cndmask_b32_e32 v16, v16, v18, vcc
	v_mov_b32_e32 v18, s19
	v_mov_b32_e32 v19, s25
	v_cndmask_b32_e32 v19, v18, v19, vcc
	v_mov_b32_e32 v18, s18
	v_mov_b32_e32 v22, s24
	v_ashrrev_i32_e32 v49, 31, v48
	v_cndmask_b32_e32 v18, v18, v22, vcc
	v_lshlrev_b64 v[22:23], 10, v[48:49]
	v_lshl_add_u64 v[18:19], v[18:19], 0, v[22:23]
	v_lshl_add_u64 v[24:25], v[108:109], 1, v[18:19]
	v_mul_f32_e32 v18, v45, v45
	v_pk_fma_f32 v[18:19], v[44:45], v[44:45], v[18:19] op_sel_hi:[1,1,0]
	v_mul_f32_e32 v22, v47, v47
	v_pk_fma_f32 v[18:19], v[46:47], v[46:47], v[18:19]
	s_mov_b32 s4, 0x800000
	v_pk_add_f32 v[18:19], v[22:23], v[18:19] op_sel_hi:[0,1]
	v_pk_fma_f32 v[18:19], v[40:41], v[40:41], v[18:19]
	v_mul_f32_e32 v22, v41, v41
	v_pk_add_f32 v[18:19], v[22:23], v[18:19] op_sel_hi:[0,1]
	v_pk_fma_f32 v[18:19], v[42:43], v[42:43], v[18:19]
	v_mul_f32_e32 v22, v43, v43
	v_pk_add_f32 v[18:19], v[22:23], v[18:19] op_sel_hi:[0,1]
	v_pk_fma_f32 v[18:19], v[36:37], v[36:37], v[18:19]
	v_mul_f32_e32 v22, v37, v37
	v_pk_add_f32 v[18:19], v[22:23], v[18:19] op_sel_hi:[0,1]
	v_pk_fma_f32 v[18:19], v[38:39], v[38:39], v[18:19]
	v_mul_f32_e32 v22, v39, v39
	v_pk_add_f32 v[18:19], v[22:23], v[18:19] op_sel_hi:[0,1]
	v_pk_fma_f32 v[18:19], v[32:33], v[32:33], v[18:19]
	v_mul_f32_e32 v22, v33, v33
	v_pk_add_f32 v[18:19], v[22:23], v[18:19] op_sel_hi:[0,1]
	v_pk_fma_f32 v[18:19], v[34:35], v[34:35], v[18:19]
	v_mul_f32_e32 v22, v35, v35
	v_pk_add_f32 v[18:19], v[22:23], v[18:19] op_sel_hi:[0,1]
	v_pk_fma_f32 v[18:19], v[12:13], v[12:13], v[18:19]
	v_mul_f32_e32 v22, v13, v13
	v_pk_add_f32 v[18:19], v[22:23], v[18:19] op_sel_hi:[0,1]
	v_pk_fma_f32 v[18:19], v[14:15], v[14:15], v[18:19]
	v_mul_f32_e32 v22, v15, v15
	v_pk_add_f32 v[18:19], v[22:23], v[18:19] op_sel_hi:[0,1]
	v_pk_fma_f32 v[18:19], v[8:9], v[8:9], v[18:19]
	v_mul_f32_e32 v22, v9, v9
	v_pk_add_f32 v[18:19], v[22:23], v[18:19] op_sel_hi:[0,1]
	v_pk_fma_f32 v[18:19], v[10:11], v[10:11], v[18:19]
	v_mul_f32_e32 v22, v11, v11
	v_pk_add_f32 v[18:19], v[22:23], v[18:19] op_sel_hi:[0,1]
	v_pk_fma_f32 v[18:19], v[4:5], v[4:5], v[18:19]
	v_mul_f32_e32 v22, v5, v5
	v_pk_add_f32 v[18:19], v[22:23], v[18:19] op_sel_hi:[0,1]
	v_pk_fma_f32 v[18:19], v[6:7], v[6:7], v[18:19]
	v_mul_f32_e32 v22, v7, v7
	v_pk_add_f32 v[18:19], v[22:23], v[18:19] op_sel_hi:[0,1]
	v_pk_fma_f32 v[18:19], v[0:1], v[0:1], v[18:19]
	v_mul_f32_e32 v22, v1, v1
	v_pk_add_f32 v[18:19], v[22:23], v[18:19] op_sel_hi:[0,1]
	v_pk_fma_f32 v[18:19], v[2:3], v[2:3], v[18:19]
	v_mul_f32_e32 v22, v3, v3
	v_pk_add_f32 v[18:19], v[22:23], v[18:19] op_sel_hi:[0,1]
	v_mov_b32_e32 v19, v18
	s_nop 1
	v_permlane32_swap_b32_e32 v18, v19
	v_add_f32_e32 v18, v18, v19
	v_fmamk_f32 v18, v18, 0x3c800000, v163
	v_cmp_gt_f32_e32 vcc, s4, v18
	v_mul_f32_e32 v19, 0x4b800000, v18
	v_lshlrev_b32_e32 v128, 2, v118
	v_cndmask_b32_e32 v18, v18, v19, vcc
	v_rsq_f32_e32 v18, v18
	v_lshl_add_u64 v[26:27], v[16:17], 0, v[128:129]
	v_mov_b32_e32 v77, v129
	v_lshl_add_u64 v[24:25], v[24:25], 0, v[76:77]
	v_mul_f32_e32 v19, 0x45800000, v18
	v_cndmask_b32_e32 v22, v18, v19, vcc
	v_pk_mul_f32 v[28:29], v[44:45], v[22:23] op_sel_hi:[1,0]
	v_cmp_ne_u64_e32 vcc, 0, v[20:21]
	s_nop 0
	v_pk_mul_f32 v[16:17], v[198:199], v[28:29]
	v_pk_mul_f32 v[28:29], v[46:47], v[22:23] op_sel_hi:[1,0]
	s_nop 0
	v_pk_mul_f32 v[18:19], v[200:201], v[28:29]
	v_cvt_pk_bf16_f32 v28, v16, v17
	v_cvt_pk_bf16_f32 v29, v18, v19
	global_store_dwordx2 v[24:25], v[28:29], off
	s_and_saveexec_b64 s[4:5], vcc
	s_cbranch_execz .LBB0_960
	v_lshl_add_u64 v[28:29], v[20:21], 0, v[128:129]
	global_store_dwordx4 v[28:29], v[16:19], off
.LBB0_960:
	s_or_b64 exec, exec, s[4:5]
	v_mov_b32_e32 v23, v22
	v_pk_mul_f32 v[28:29], v[40:41], v[22:23]
	v_pk_mul_f32 v[30:31], v[42:43], v[22:23]
	s_nop 0
	v_pk_mul_f32 v[16:17], v[28:29], v[202:203]
	v_pk_mul_f32 v[18:19], v[30:31], v[204:205]
	v_cvt_pk_bf16_f32 v28, v16, v17
	v_cvt_pk_bf16_f32 v29, v18, v19
	global_store_dwordx2 v[24:25], v[28:29], off offset:16
	s_and_saveexec_b64 s[4:5], vcc
	s_cbranch_execz .LBB0_962
	v_lshl_add_u64 v[28:29], v[20:21], 0, v[128:129]
	global_store_dwordx4 v[28:29], v[16:19], off offset:32
.LBB0_962:
	s_or_b64 exec, exec, s[4:5]
	v_pk_mul_f32 v[28:29], v[36:37], v[22:23]
	v_pk_mul_f32 v[30:31], v[38:39], v[22:23]
	s_nop 0
	v_pk_mul_f32 v[16:17], v[28:29], v[206:207]
	v_pk_mul_f32 v[18:19], v[30:31], v[208:209]
	v_cvt_pk_bf16_f32 v28, v16, v17
	v_cvt_pk_bf16_f32 v29, v18, v19
	global_store_dwordx2 v[24:25], v[28:29], off offset:32
	s_and_saveexec_b64 s[4:5], vcc
	s_cbranch_execz .LBB0_964
	v_lshl_add_u64 v[28:29], v[20:21], 0, v[128:129]
	global_store_dwordx4 v[28:29], v[16:19], off offset:64
.LBB0_964:
	s_or_b64 exec, exec, s[4:5]
	v_pk_mul_f32 v[28:29], v[32:33], v[22:23]
	v_pk_mul_f32 v[30:31], v[34:35], v[22:23]
	s_nop 0
	v_pk_mul_f32 v[16:17], v[28:29], v[210:211]
	v_pk_mul_f32 v[18:19], v[30:31], v[212:213]
	v_cvt_pk_bf16_f32 v28, v16, v17
	v_cvt_pk_bf16_f32 v29, v18, v19
	global_store_dwordx2 v[24:25], v[28:29], off offset:48
	s_and_saveexec_b64 s[4:5], vcc
	s_cbranch_execz .LBB0_966
	v_lshl_add_u64 v[28:29], v[20:21], 0, v[128:129]
	global_store_dwordx4 v[28:29], v[16:19], off offset:96
.LBB0_966:
	s_or_b64 exec, exec, s[4:5]
	v_pk_mul_f32 v[12:13], v[12:13], v[22:23]
	v_pk_mul_f32 v[14:15], v[14:15], v[22:23]
	s_nop 0
	v_pk_mul_f32 v[12:13], v[12:13], v[214:215]
	v_pk_mul_f32 v[14:15], v[14:15], v[216:217]
	v_cvt_pk_bf16_f32 v16, v12, v13
	v_cvt_pk_bf16_f32 v17, v14, v15
	global_store_dwordx2 v[24:25], v[16:17], off offset:64
	s_and_saveexec_b64 s[4:5], vcc
	s_cbranch_execz .LBB0_968
	v_lshl_add_u64 v[16:17], v[20:21], 0, v[128:129]
	global_store_dwordx4 v[16:17], v[12:15], off offset:128
.LBB0_968:
	s_or_b64 exec, exec, s[4:5]
	v_pk_mul_f32 v[8:9], v[8:9], v[22:23]
	v_pk_mul_f32 v[10:11], v[10:11], v[22:23]
	s_nop 0
	v_pk_mul_f32 v[8:9], v[8:9], v[218:219]
	v_pk_mul_f32 v[10:11], v[10:11], v[220:221]
	v_cvt_pk_bf16_f32 v12, v8, v9
	v_cvt_pk_bf16_f32 v13, v10, v11
	global_store_dwordx2 v[24:25], v[12:13], off offset:80
	s_and_saveexec_b64 s[4:5], vcc
	s_cbranch_execz .LBB0_970
	v_lshl_add_u64 v[12:13], v[20:21], 0, v[128:129]
	global_store_dwordx4 v[12:13], v[8:11], off offset:160
.LBB0_970:
	s_or_b64 exec, exec, s[4:5]
	v_pk_mul_f32 v[4:5], v[4:5], v[22:23]
	v_pk_mul_f32 v[6:7], v[6:7], v[22:23]
	s_nop 0
	v_pk_mul_f32 v[4:5], v[4:5], v[222:223]
	v_pk_mul_f32 v[6:7], v[6:7], v[224:225]
	v_cvt_pk_bf16_f32 v8, v4, v5
	v_cvt_pk_bf16_f32 v9, v6, v7
	global_store_dwordx2 v[24:25], v[8:9], off offset:96
	s_and_saveexec_b64 s[4:5], vcc
	s_cbranch_execz .LBB0_972
	v_lshl_add_u64 v[8:9], v[20:21], 0, v[128:129]
	global_store_dwordx4 v[8:9], v[4:7], off offset:192
.LBB0_972:
	s_or_b64 exec, exec, s[4:5]
	v_pk_mul_f32 v[0:1], v[0:1], v[22:23]
	v_pk_mul_f32 v[2:3], v[2:3], v[22:23]
	s_nop 0
	v_pk_mul_f32 v[0:1], v[0:1], v[226:227]
	v_pk_mul_f32 v[2:3], v[2:3], v[228:229]
	v_cvt_pk_bf16_f32 v4, v0, v1
	v_cvt_pk_bf16_f32 v5, v2, v3
	global_store_dwordx2 v[24:25], v[4:5], off offset:112
	s_and_saveexec_b64 s[4:5], vcc
	s_cbranch_execz .LBB0_974
	v_lshl_add_u64 v[4:5], v[20:21], 0, v[128:129]
	global_store_dwordx4 v[4:5], v[0:3], off offset:224
